# baseline (speedup 1.0000x reference)
;     __device__ __forceinline__ void operator()(const AccT& acc, const pg8::Unit& u, int ui, int wr, int wc, int fr, int fq) const {
;         const int row0 = u.pm * 256 + wr * 64 + fr, col0 = u.pn * 256 + wc * 32 + 8 * fq;
; #pragma unroll
;         for (int ai = 0; ai < 2; ++ai) {
.LBB0_383:
	s_mov_b32 s101, s62
	s_mov_b32 s99, 0

; __device__ __forceinline__ unsigned pk2(float lo, float hi) { unsigned r; asm("v_cvt_pk_bf16_f32 %0, %1, %2" : "=v"(r) : "v"(lo), "v"(hi)); return r; }
; __device__ __forceinline__ float bflo(unsigned w) { return __uint_as_float(w << 16); }
; __device__ __forceinline__ float bfhi(unsigned w) { return __uint_as_float(w & 0xffff0000u); }
;     __device__ __forceinline__ void operator()(const AccT& acc, const pg8::Unit& u, int ui, int wr, int wc, int fr, int fq) const {
;     ...
;         for (int ai = 0; ai < 2; ++ai) {
;             u32x4 hv[4][2];
; #pragma unroll
;             for (int m = 0; m < 4; ++m)
; #pragma unroll
;                 for (int bj = 0; bj < 2; ++bj) hv[m][bj] = *(const u32x4*)(hin + (size_t)(row0 + ai * 128 + m * 16) * D + col0 + 128 * bj);
; #pragma unroll
;             for (int m = 0; m < 4; ++m) {
;                 const int r = row0 + ai * 128 + m * 16; float ss = 0.f;
; #pragma unroll
;                 for (int bj = 0; bj < 2; ++bj) {
;                     const u32x4 w0 = hv[m][bj];
;                     f32x4 a = {bflo(w0.x), bfhi(w0.x), bflo(w0.y), bfhi(w0.y)}, b = {bflo(w0.z), bfhi(w0.z), bflo(w0.w), bfhi(w0.w)};
;                     a += acc[ai][bj][m][0] * scale; b += acc[ai][bj][m][1] * scale;
;                     ss += (a.x * a.x + a.y * a.y) + (a.z * a.z + a.w * a.w) + (b.x * b.x + b.y * b.y) + (b.z * b.z + b.w * b.w);
;                     u32x4 w; w.x = pk2(a.x, a.y); w.y = pk2(a.z, a.w); w.z = pk2(b.x, b.y); w.w = pk2(b.z, b.w); *(u32x4*)(hb + (size_t)r * D + col0 + 128 * bj) = w;
;                 }
;                 ss += __shfl_xor(ss, 16); ss += __shfl_xor(ss, 32); if (fq == 0) part_out[(size_t)r * 16 + u.pn * 4 + wc] = ss;
;             }
;         }
.LBB0_391:
	s_or_b64 exec, exec, s[10:11]
	s_cmp_lg_u32 s99, 0
	s_cbranch_scc1 .Lfold_d_done
	s_mov_b32 s99, 1
	s_mov_b32 s62, s101
	s_add_i32 s53, s53, 0x80
	s_nop 1
	v_mov_b64_e32 v[142:143], v[62:63]
	v_mov_b64_e32 v[144:145], v[64:65]
	v_mov_b64_e32 v[138:139], v[58:59]
	v_mov_b64_e32 v[140:141], v[60:61]
	v_mov_b64_e32 v[110:111], v[46:47]
	v_mov_b64_e32 v[112:113], v[48:49]
	v_mov_b64_e32 v[106:107], v[42:43]
	v_mov_b64_e32 v[108:109], v[44:45]
	v_mov_b64_e32 v[94:95], v[30:31]
	v_mov_b64_e32 v[96:97], v[32:33]
	v_mov_b64_e32 v[90:91], v[26:27]
	v_mov_b64_e32 v[92:93], v[28:29]
	v_mov_b64_e32 v[78:79], v[14:15]
	v_mov_b64_e32 v[80:81], v[16:17]
	v_mov_b64_e32 v[74:75], v[10:11]
	v_mov_b64_e32 v[76:77], v[12:13]
	v_mov_b64_e32 v[130:131], v[54:55]
	v_mov_b64_e32 v[132:133], v[56:57]
	v_mov_b64_e32 v[126:127], v[50:51]
	v_mov_b64_e32 v[128:129], v[52:53]
	v_mov_b64_e32 v[102:103], v[38:39]
	v_mov_b64_e32 v[104:105], v[40:41]
	v_mov_b64_e32 v[98:99], v[34:35]
	v_mov_b64_e32 v[100:101], v[36:37]
	v_mov_b64_e32 v[86:87], v[22:23]
	v_mov_b64_e32 v[88:89], v[24:25]
	v_mov_b64_e32 v[82:83], v[18:19]
	v_mov_b64_e32 v[84:85], v[20:21]
	v_mov_b64_e32 v[70:71], v[6:7]
	v_mov_b64_e32 v[72:73], v[8:9]
	v_mov_b64_e32 v[66:67], v[2:3]
	v_mov_b64_e32 v[68:69], v[4:5]
	s_branch .Lfold_d_again
.Lfold_d_done:
	s_sub_i32 s53, s53, 0x80
